# select phase: one static priority raise for waves 4-7 (dropped at the phase exit)
# speedup vs baseline: 1.0012x; 1.0012x over previous
; __device__ __forceinline__ int opaque_tid() { int t = threadIdx.x; asm volatile("" : "+v"(t)); return t; }
; #define LAS __attribute__((address_space(3)))
; DI void phase_peer_select(const Args& a, int layer, LAS unsigned char* lds) {
;     const int tid = opaque_tid(), lane = tid & 63, wave = tid >> 6;
;     const int gw = blockIdx.x * 8 + wave, NGW = gridDim.x * 8;
;     unsigned char* ws = a.ws;
;     const bf16_t* Q2 = (const bf16_t*)(ws + WS_Q2);
;     const bf16_t* subk = (const bf16_t*)(ws + WS_SUBK) + (size_t)layer * 2 * 128 * 128;
;     int* IDX = (int*)(ws + WS_IDX);
;     float* GATE = (float*)(ws + WS_GATE);
;     LAS unsigned* lt1 = (LAS unsigned*)(lds + wave * 8192);
;     LAS unsigned* lt2 = lt1 + 1024;
;     const int c = lane & 31, hi = lane >> 5, tl = c >> 3, h = c & 7;
; #pragma unroll 1
;     for (int unit = gw; unit < M / 4; unit += NGW) {
;         const size_t m = (size_t)unit * 4 + tl;
;         const bf16_t* qrow = Q2 + m * D + h * 256 + hi * 8;
; __global__ void __launch_bounds__(NTHREADS, 2) hybrid_fwd(Args a) {
;     ...
;         else {
;             const int layer = (ph - 1) / PH_PER_LAYER, k = (ph - 1) % PH_PER_LAYER;
;             if (k == 0) run_phase<1>(a, layer, lds);
;             else if (k == 1) run_phase<2>(a, layer, lds);
;             else if (k == 2) run_phase<3>(a, layer, lds);
;             else if (k == 3) run_phase<4>(a, layer, lds);
;             else if (k == 4) run_phase<5>(a, layer, lds);
;             else if (k == 5) run_phase<6>(a, layer, lds);
;             else if (k == 6) run_phase<7>(a, layer, lds);
;             else if (k == 7) run_phase<8>(a, layer, lds);
;             else if (k < 10) run_phase<9>(a, layer, lds, k - 8);
;             else run_phase<14>(a, layer, lds, k - 10);
.LBB0_33:
	s_add_i32 s0, s62, -1
	s_mul_hi_i32 s1, s0, 0x2aaaaaab
	s_lshr_b32 s8, s1, 31
	s_ashr_i32 s1, s1, 1
	s_add_i32 s16, s1, s8
	s_mov_b32 s8, s16
	v_writelane_b32 v255, s8, 12
	s_mul_i32 s1, s16, 12
	s_nop 0
	v_writelane_b32 v255, s9, 13
	s_sub_i32 s8, s0, s1
	v_writelane_b32 v255, s8, 14
	s_cmp_lt_i32 s8, 4
	s_mov_b64 s[8:9], 0
	v_writelane_b32 v255, s8, 15
	s_mov_b64 s[0:1], -1
	s_nop 0
	v_writelane_b32 v255, s9, 16
	v_writelane_b32 v255, s62, 17
	s_nop 1
	v_writelane_b32 v255, s63, 18
	s_cbranch_scc1 .LBB0_118
	v_readlane_b32 s0, v255, 14
	s_cmp_gt_i32 s0, 5
	s_cbranch_scc0 .LBB0_50
	s_cmp_gt_i32 s0, 6
	s_cbranch_scc0 .LBB0_51
	s_cmp_eq_u32 s0, 7
	s_mov_b64 s[0:1], -1
	s_cbranch_scc0 .LBB0_53
	v_mov_b32_e32 v0, v185
	v_readlane_b32 s0, v252, 34
	s_waitcnt lgkmcnt(0)
	v_ashrrev_i32_e32 v1, 6, v0
	v_add_u32_e32 v48, s0, v1
	s_movk_i32 s0, 0x2000
	v_cmp_gt_i32_e32 vcc, s0, v48
	s_and_saveexec_b64 s[44:45], vcc
	s_cbranch_execz .LBB0_52
	v_readlane_b32 s0, v252, 5
	v_readlane_b32 s1, v252, 6
	s_load_dword s0, s[0:1], 0x0
	v_and_b32_e32 v4, 7, v0
	v_bfe_u32 v6, v0, 5, 1
	v_lshlrev_b32_e32 v128, 9, v4
	v_lshlrev_b32_e32 v2, 13, v1
	s_waitcnt lgkmcnt(0)
	s_lshl_b32 s46, s0, 3
	v_readlane_b32 s0, v255, 12
	v_readlane_b32 s1, v255, 13
	s_mov_b32 s8, s0
	s_ashr_i32 s9, s0, 31
	v_writelane_b32 v255, s0, 12
	v_and_b32_e32 v3, 63, v0
	v_and_b32_e32 v5, 31, v0
	v_writelane_b32 v255, s1, 13
	s_lshl_b64 s[0:1], s[8:9], 16
	v_readlane_b32 s8, v252, 19
	s_add_u32 s0, s8, s0
	v_readlane_b32 s8, v252, 20
	s_addc_u32 s1, s8, s1
	v_readlane_b32 s8, v252, 25
	v_readlane_b32 s9, v252, 26
	v_bfe_u32 v50, v0, 3, 2
	v_ashrrev_i32_e32 v49, 31, v48
	v_lshl_add_u64 v[0:1], s[8:9], 0, v[128:129]
	v_lshlrev_b32_e32 v128, 4, v6
	v_lshl_add_u64 v[52:53], v[0:1], 0, v[128:129]
	v_lshlrev_b32_e32 v0, 8, v5
	v_mov_b32_e32 v1, v129
	v_lshl_add_u64 v[0:1], s[0:1], 0, v[0:1]
	v_lshl_add_u64 v[54:55], v[0:1], 0, v[128:129]
	v_mov_b32_e32 v0, 0x7e
	v_mad_i32_i24 v51, v6, -4, v0
	v_mov_b32_e32 v0, 0x7f
	v_mad_i32_i24 v56, v6, -4, v0
	v_mov_b32_e32 v0, 0x7c
	v_mad_i32_i24 v57, v6, -4, v0
	v_mov_b32_e32 v0, 0x7d
	v_mad_i32_i24 v58, v6, -4, v0
	v_mov_b32_e32 v0, 0x76
	v_mad_i32_i24 v59, v6, -4, v0
	v_mov_b32_e32 v0, 0x77
	v_mad_i32_i24 v60, v6, -4, v0
	v_mov_b32_e32 v0, 0x74
	v_mad_i32_i24 v61, v6, -4, v0
	v_mov_b32_e32 v0, 0x75
	v_mad_i32_i24 v62, v6, -4, v0
	v_mov_b32_e32 v0, 0x6e
	v_mad_i32_i24 v63, v6, -4, v0
	v_mov_b32_e32 v0, 0x6f
	v_mad_i32_i24 v64, v6, -4, v0
	v_mov_b32_e32 v0, 0x6c
	v_mad_i32_i24 v65, v6, -4, v0
	v_mov_b32_e32 v0, 0x6d
	v_mad_i32_i24 v66, v6, -4, v0
	v_mov_b32_e32 v0, 0x66
	v_mad_i32_i24 v67, v6, -4, v0
	v_mov_b32_e32 v0, 0x67
	v_mad_i32_i24 v68, v6, -4, v0
	v_mov_b32_e32 v0, 0x64
	v_mad_i32_i24 v69, v6, -4, v0
	v_mov_b32_e32 v0, 0x65
	v_mad_i32_i24 v70, v6, -4, v0
	v_mov_b32_e32 v0, 0x5e
	v_mad_i32_i24 v71, v6, -4, v0
	v_mov_b32_e32 v0, 0x5f
	v_mad_i32_i24 v72, v6, -4, v0
	v_mov_b32_e32 v0, 0x5c
	v_mad_i32_i24 v73, v6, -4, v0
	v_mov_b32_e32 v0, 0x5d
	v_mad_i32_i24 v74, v6, -4, v0
	v_mov_b32_e32 v0, 0x56
	v_mad_i32_i24 v75, v6, -4, v0
	v_mov_b32_e32 v0, 0x57
	v_mad_i32_i24 v76, v6, -4, v0
	v_mov_b32_e32 v0, 0x54
	v_mad_i32_i24 v77, v6, -4, v0
	v_mov_b32_e32 v0, 0x55
	v_mad_i32_i24 v78, v6, -4, v0
	v_mov_b32_e32 v0, 0x4e
	v_mad_i32_i24 v79, v6, -4, v0
	v_mov_b32_e32 v0, 0x4f
	v_mad_i32_i24 v80, v6, -4, v0
	v_mov_b32_e32 v0, 0x4c
	v_mad_i32_i24 v81, v6, -4, v0
	v_mov_b32_e32 v0, 0x4d
	v_mad_i32_i24 v82, v6, -4, v0
	v_mov_b32_e32 v0, 0x46
	v_mad_i32_i24 v83, v6, -4, v0
	v_mov_b32_e32 v0, 0x47
	v_mad_i32_i24 v84, v6, -4, v0
	v_mov_b32_e32 v0, 0x44
	s_mov_b64 s[0:1], 0x8000
	v_mad_i32_i24 v85, v6, -4, v0
	v_mov_b32_e32 v0, 0x45
	v_lshl_add_u64 v[120:121], v[54:55], 0, s[0:1]
	v_readlane_b32 s0, v252, 27
	v_mad_i32_i24 v86, v6, -4, v0
	v_lshlrev_b32_e32 v0, 2, v3
	v_lshlrev_b32_e32 v128, 2, v4
	v_readlane_b32 s1, v252, 28
	v_add3_u32 v216, 0, v2, v0
	v_or_b32_e32 v0, v2, v0
	v_lshl_add_u64 v[122:123], s[0:1], 0, v[128:129]
	v_readlane_b32 s0, v254, 62
	v_cmp_gt_u32_e64 s[38:39], 32, v3
	v_lshlrev_b32_e32 v2, 9, v50
	v_add_u32_e32 v217, s0, v0
	v_lshlrev_b64 v[0:1], 11, v[48:49]
	v_lshlrev_b32_e32 v3, 6, v4
	v_or3_b32 v0, v0, v2, v3
	s_ashr_i32 s47, s46, 31
	v_mad_i32_i24 v87, v6, -4, 62
	v_mad_i32_i24 v88, v6, -4, 63
	v_mad_i32_i24 v89, v6, -4, 60
	v_mad_i32_i24 v90, v6, -4, 61
	v_mad_i32_i24 v91, v6, -4, 54
	v_mad_i32_i24 v92, v6, -4, 55
	v_mad_i32_i24 v93, v6, -4, 52
	v_mad_i32_i24 v94, v6, -4, 53
	v_mad_i32_i24 v95, v6, -4, 46
	v_mad_i32_i24 v96, v6, -4, 47
	v_mad_i32_i24 v97, v6, -4, 44
	v_mad_i32_i24 v98, v6, -4, 45
	v_mad_i32_i24 v99, v6, -4, 38
	v_mad_i32_i24 v100, v6, -4, 39
	v_mad_i32_i24 v101, v6, -4, 36
	v_mad_i32_i24 v102, v6, -4, 37
	v_mad_i32_i24 v103, v6, -4, 30
	v_mad_i32_i24 v104, v6, -4, 31
	v_mad_i32_i24 v105, v6, -4, 28
	v_mad_i32_i24 v106, v6, -4, 29
	v_mad_i32_i24 v107, v6, -4, 22
	v_mad_i32_i24 v108, v6, -4, 23
	v_mad_i32_i24 v109, v6, -4, 20
	v_mad_i32_i24 v110, v6, -4, 21
	v_mad_i32_i24 v111, v6, -4, 14
	v_mad_i32_i24 v112, v6, -4, 15
	v_mad_i32_i24 v113, v6, -4, 12
	v_mad_i32_i24 v114, v6, -4, 13
	v_mad_i32_i24 v115, v6, -4, 6
	v_mad_i32_i24 v116, v6, -4, 7
	v_mad_i32_i24 v117, v6, -4, 4
	v_mad_i32_i24 v118, v6, -4, 5
	v_lshl_add_u64 v[124:125], s[98:99], 0, v[0:1]
	s_lshl_b64 s[48:49], s[46:47], 11
	s_mov_b64 s[50:51], 0
	v_readfirstlane_b32 s100, v185
	s_nop 3
	s_lshr_b32 s100, s100, 6
	s_cmp_ge_u32 s100, 4
	s_cbranch_scc0 .Lp_sprio_done
	s_setprio 1
.Lp_sprio_done:
	s_branch .LBB0_40
.LBB0_39:
	s_or_b64 exec, exec, s[0:1]
	s_waitcnt lgkmcnt(0)
	v_add_u32_e32 v48, s46, v48
	s_movk_i32 s0, 0x1fff
	v_cmp_lt_i32_e32 vcc, s0, v48
	s_or_b64 s[50:51], vcc, s[50:51]
	v_lshl_add_u64 v[124:125], v[124:125], 0, s[48:49]
	s_andn2_b64 exec, exec, s[50:51]
	s_cbranch_execz .LBB0_52

; DI void phase_peer_select(const Args& a, int layer, LAS unsigned char* lds) {
;     ...
;     }
; }
.LBB0_52:
	s_setprio 0
	s_or_b64 exec, exec, s[44:45]
	s_mov_b64 s[0:1], 0
